# v23 + GEMM K-loop back-edge SALU blocks above the loop-back barrier + peel drain wait moved to just before the first epilogue store
# baseline (speedup 1.0000x reference)
.LBB0_151:
	s_and_b32 s15, s47, 1
	v_lshl_add_u32 v150, s15, 10, v146
	ds_read_b32 v152, v150
	v_mov_b32_e32 v154, v122
	v_mov_b32_e32 v155, v126
	v_mov_b32_e32 v126, v123
	v_lshl_or_b32 v140, s23, 7, v144
	s_waitcnt lgkmcnt(0)
	v_pk_mul_f32 v[154:155], v[154:155], v[152:153] op_sel_hi:[1,0]
	v_lshl_add_u32 v149, s22, 8, v142
	v_mul_f32_e32 v122, 0xbfb8aa3b, v155
	v_exp_f32_e32 v122, v122
	v_ashrrev_i32_e32 v141, 31, v140
	s_andn2_b64 vcc, exec, s[2:3]
	v_add_f32_e32 v122, 1.0, v122
	v_rcp_f32_e32 v122, v122
	s_nop 0
	v_mul_f32_e32 v122, v155, v122
	v_mul_f32_e32 v151, v154, v122
	v_pk_mul_f32 v[122:123], v[126:127], v[152:153] op_sel_hi:[1,0]
	s_nop 0
	v_mul_f32_e32 v126, 0xbfb8aa3b, v123
	v_exp_f32_e32 v126, v126
	s_nop 0
	v_add_f32_e32 v126, 1.0, v126
	v_rcp_f32_e32 v126, v126
	s_nop 0
	v_mul_f32_e32 v123, v123, v126
	v_mul_f32_e32 v126, v122, v123
	v_mov_b32_e32 v122, v124
	v_mov_b32_e32 v123, v128
	v_pk_mul_f32 v[122:123], v[122:123], v[152:153] op_sel_hi:[1,0]
	v_mov_b32_e32 v128, v125
	v_mul_f32_e32 v124, 0xbfb8aa3b, v123
	v_exp_f32_e32 v124, v124
	s_nop 0
	v_add_f32_e32 v124, 1.0, v124
	v_rcp_f32_e32 v124, v124
	s_nop 0
	v_mul_f32_e32 v123, v123, v124
	v_mul_f32_e32 v124, v122, v123
	v_pk_mul_f32 v[122:123], v[128:129], v[152:153] op_sel_hi:[1,0]
	s_nop 0
	v_mul_f32_e32 v125, 0xbfb8aa3b, v123
	v_exp_f32_e32 v125, v125
	s_nop 0
	v_add_f32_e32 v125, 1.0, v125
	v_rcp_f32_e32 v125, v125
	s_nop 0
	v_mul_f32_e32 v123, v123, v125
	v_mul_f32_e32 v125, v122, v123
	v_mov_b32_e32 v122, v114
	v_mov_b32_e32 v123, v118
	v_pk_mul_f32 v[122:123], v[122:123], v[152:153] op_sel_hi:[1,0]
	v_mov_b32_e32 v118, v115
	v_mul_f32_e32 v114, 0xbfb8aa3b, v123
	v_exp_f32_e32 v114, v114
	s_nop 0
	v_add_f32_e32 v114, 1.0, v114
	v_rcp_f32_e32 v114, v114
	s_nop 0
	v_mul_f32_e32 v114, v123, v114
	v_mul_f32_e32 v122, v122, v114
	v_pk_mul_f32 v[114:115], v[118:119], v[152:153] op_sel_hi:[1,0]
	s_nop 0
	v_mul_f32_e32 v118, 0xbfb8aa3b, v115
	v_exp_f32_e32 v118, v118
	s_nop 0
	v_add_f32_e32 v118, 1.0, v118
	v_rcp_f32_e32 v118, v118
	s_nop 0
	v_mul_f32_e32 v115, v115, v118
	v_mul_f32_e32 v123, v114, v115
	v_mov_b32_e32 v114, v116
	v_mov_b32_e32 v115, v120
	v_pk_mul_f32 v[114:115], v[114:115], v[152:153] op_sel_hi:[1,0]
	v_mov_b32_e32 v120, v117
	v_mul_f32_e32 v116, 0xbfb8aa3b, v115
	v_exp_f32_e32 v116, v116
	v_cvt_pk_bf16_f32 v118, v151, v126
	v_cvt_pk_bf16_f32 v119, v124, v125
	s_nop 0
	v_add_f32_e32 v116, 1.0, v116
	v_rcp_f32_e32 v116, v116
	s_nop 0
	v_mul_f32_e32 v115, v115, v116
	v_mul_f32_e32 v116, v114, v115
	v_pk_mul_f32 v[114:115], v[120:121], v[152:153] op_sel_hi:[1,0]
	v_cvt_pk_bf16_f32 v120, v122, v123
	s_nop 0
	v_mul_f32_e32 v117, 0xbfb8aa3b, v115
	v_exp_f32_e32 v117, v117
	s_nop 0
	v_add_f32_e32 v117, 1.0, v117
	v_rcp_f32_e32 v117, v117
	s_nop 0
	v_mul_f32_e32 v115, v115, v117
	v_mul_f32_e32 v114, v114, v115
	v_cvt_pk_bf16_f32 v121, v116, v114
	v_mov_b64_e32 v[114:115], s[8:9]
	v_mad_i64_i32 v[122:123], s[22:23], v149, s89, v[114:115]
	v_lshlrev_b64 v[116:117], 1, v[140:141]
	v_lshl_add_u64 v[122:123], v[122:123], 0, v[116:117]
	s_waitcnt vmcnt(0)
	global_store_dwordx4 v[122:123], v[118:121], off sc1
	s_nop 1
	ds_read_b32 v118, v150 offset:64
	v_mov_b32_e32 v120, v106
	v_mov_b32_e32 v121, v110
	v_mov_b32_e32 v110, v107
	s_waitcnt lgkmcnt(0)
	v_pk_mul_f32 v[120:121], v[120:121], v[118:119] op_sel_hi:[1,0]
	s_nop 0
	v_mul_f32_e32 v106, 0xbfb8aa3b, v121
	v_exp_f32_e32 v106, v106
	s_nop 0
	v_add_f32_e32 v106, 1.0, v106
	v_rcp_f32_e32 v106, v106
	s_nop 0
	v_mul_f32_e32 v106, v121, v106
	v_mul_f32_e32 v119, v120, v106
	v_pk_mul_f32 v[106:107], v[110:111], v[118:119] op_sel_hi:[1,0]
	s_nop 0
	v_mul_f32_e32 v110, 0xbfb8aa3b, v107
	v_exp_f32_e32 v110, v110
	s_nop 0
	v_add_f32_e32 v110, 1.0, v110
	v_rcp_f32_e32 v110, v110
	s_nop 0
	v_mul_f32_e32 v107, v107, v110
	v_mul_f32_e32 v110, v106, v107
	v_mov_b32_e32 v106, v108
	v_mov_b32_e32 v107, v112
	v_pk_mul_f32 v[106:107], v[106:107], v[118:119] op_sel_hi:[1,0]
	v_mov_b32_e32 v112, v109
	v_mul_f32_e32 v108, 0xbfb8aa3b, v107
	v_exp_f32_e32 v108, v108
	s_nop 0
	v_add_f32_e32 v108, 1.0, v108
	v_rcp_f32_e32 v108, v108
	s_nop 0
	v_mul_f32_e32 v107, v107, v108
	v_mul_f32_e32 v108, v106, v107
	v_pk_mul_f32 v[106:107], v[112:113], v[118:119] op_sel_hi:[1,0]
	s_nop 0
	v_mul_f32_e32 v109, 0xbfb8aa3b, v107
	v_exp_f32_e32 v109, v109
	s_nop 0
	v_add_f32_e32 v109, 1.0, v109
	v_rcp_f32_e32 v109, v109
	s_nop 0
	v_mul_f32_e32 v107, v107, v109
	v_mul_f32_e32 v109, v106, v107
	v_mov_b32_e32 v106, v98
	v_mov_b32_e32 v107, v102
	v_pk_mul_f32 v[106:107], v[106:107], v[118:119] op_sel_hi:[1,0]
	v_mov_b32_e32 v102, v99
	v_mul_f32_e32 v98, 0xbfb8aa3b, v107
	v_exp_f32_e32 v98, v98
	s_nop 0
	v_add_f32_e32 v98, 1.0, v98
	v_rcp_f32_e32 v98, v98
	s_nop 0
	v_mul_f32_e32 v98, v107, v98
	v_mul_f32_e32 v106, v106, v98
	v_pk_mul_f32 v[98:99], v[102:103], v[118:119] op_sel_hi:[1,0]
	s_nop 0
	v_mul_f32_e32 v102, 0xbfb8aa3b, v99
	v_exp_f32_e32 v102, v102
	s_nop 0
	v_add_f32_e32 v102, 1.0, v102
	v_rcp_f32_e32 v102, v102
	s_nop 0
	v_mul_f32_e32 v99, v99, v102
	v_mul_f32_e32 v102, v98, v99
	v_mov_b32_e32 v98, v100
	v_mov_b32_e32 v99, v104
	v_pk_mul_f32 v[98:99], v[98:99], v[118:119] op_sel_hi:[1,0]
	v_mov_b32_e32 v104, v101
	v_mul_f32_e32 v100, 0xbfb8aa3b, v99
	v_exp_f32_e32 v100, v100
	s_nop 0
	v_add_f32_e32 v100, 1.0, v100
	v_rcp_f32_e32 v100, v100
	s_nop 0
	v_mul_f32_e32 v99, v99, v100
	v_mul_f32_e32 v103, v98, v99
	v_pk_mul_f32 v[98:99], v[104:105], v[118:119] op_sel_hi:[1,0]
	v_or_b32_e32 v104, 16, v149
	v_mul_f32_e32 v100, 0xbfb8aa3b, v99
	v_exp_f32_e32 v100, v100
	s_nop 0
	v_add_f32_e32 v100, 1.0, v100
	v_rcp_f32_e32 v100, v100
	s_nop 0
	v_mul_f32_e32 v99, v99, v100
	v_mul_f32_e32 v101, v98, v99
	v_cvt_pk_bf16_f32 v98, v119, v110
	v_cvt_pk_bf16_f32 v99, v108, v109
	v_cvt_pk_bf16_f32 v100, v106, v102
	v_cvt_pk_bf16_f32 v101, v103, v101
	v_mad_i64_i32 v[102:103], s[22:23], v104, s89, v[114:115]
	v_lshl_add_u64 v[102:103], v[102:103], 0, v[116:117]
	global_store_dwordx4 v[102:103], v[98:101], off sc1
	s_nop 1
	ds_read_b32 v98, v150 offset:128
	v_mov_b32_e32 v100, v88
	v_mov_b32_e32 v101, v92
	v_mov_b32_e32 v92, v89
	s_waitcnt lgkmcnt(0)
	v_pk_mul_f32 v[100:101], v[100:101], v[98:99] op_sel_hi:[1,0]
	s_nop 0
	v_mul_f32_e32 v88, 0xbfb8aa3b, v101
	v_exp_f32_e32 v88, v88
	s_nop 0
	v_add_f32_e32 v88, 1.0, v88
	v_rcp_f32_e32 v88, v88
	s_nop 0
	v_mul_f32_e32 v88, v101, v88
	v_mul_f32_e32 v99, v100, v88
	v_pk_mul_f32 v[88:89], v[92:93], v[98:99] op_sel_hi:[1,0]
	s_nop 0
	v_mul_f32_e32 v92, 0xbfb8aa3b, v89
	v_exp_f32_e32 v92, v92
	s_nop 0
	v_add_f32_e32 v92, 1.0, v92
	v_rcp_f32_e32 v92, v92
	s_nop 0
	v_mul_f32_e32 v89, v89, v92
	v_mul_f32_e32 v92, v88, v89
	v_mov_b32_e32 v88, v90
	v_mov_b32_e32 v89, v94
	v_pk_mul_f32 v[88:89], v[88:89], v[98:99] op_sel_hi:[1,0]
	v_mov_b32_e32 v94, v91
	v_mul_f32_e32 v90, 0xbfb8aa3b, v89
	v_exp_f32_e32 v90, v90
	s_nop 0
	v_add_f32_e32 v90, 1.0, v90
	v_rcp_f32_e32 v90, v90
	s_nop 0
	v_mul_f32_e32 v89, v89, v90
	v_mul_f32_e32 v90, v88, v89
	v_pk_mul_f32 v[88:89], v[94:95], v[98:99] op_sel_hi:[1,0]
	s_nop 0
	v_mul_f32_e32 v91, 0xbfb8aa3b, v89
	v_exp_f32_e32 v91, v91
	s_nop 0
	v_add_f32_e32 v91, 1.0, v91
	v_rcp_f32_e32 v91, v91
	s_nop 0
	v_mul_f32_e32 v89, v89, v91
	v_mul_f32_e32 v91, v88, v89
	v_mov_b32_e32 v88, v80
	v_mov_b32_e32 v89, v84
	v_pk_mul_f32 v[88:89], v[88:89], v[98:99] op_sel_hi:[1,0]
	v_mov_b32_e32 v84, v81
	v_mul_f32_e32 v80, 0xbfb8aa3b, v89
	v_exp_f32_e32 v80, v80
	s_nop 0
	v_add_f32_e32 v80, 1.0, v80
	v_rcp_f32_e32 v80, v80
	s_nop 0
	v_mul_f32_e32 v80, v89, v80
	v_mul_f32_e32 v88, v88, v80
	v_pk_mul_f32 v[80:81], v[84:85], v[98:99] op_sel_hi:[1,0]
	s_nop 0
	v_mul_f32_e32 v84, 0xbfb8aa3b, v81
	v_exp_f32_e32 v84, v84
	s_nop 0
	v_add_f32_e32 v84, 1.0, v84
	v_rcp_f32_e32 v84, v84
	s_nop 0
	v_mul_f32_e32 v81, v81, v84
	v_mul_f32_e32 v84, v80, v81
	v_mov_b32_e32 v80, v82
	v_mov_b32_e32 v81, v86
	v_pk_mul_f32 v[80:81], v[80:81], v[98:99] op_sel_hi:[1,0]
	v_mov_b32_e32 v86, v83
	v_mul_f32_e32 v82, 0xbfb8aa3b, v81
	v_exp_f32_e32 v82, v82
	s_nop 0
	v_add_f32_e32 v82, 1.0, v82
	v_rcp_f32_e32 v82, v82
	s_nop 0
	v_mul_f32_e32 v81, v81, v82
	v_mul_f32_e32 v85, v80, v81
	v_pk_mul_f32 v[80:81], v[86:87], v[98:99] op_sel_hi:[1,0]
	v_or_b32_e32 v86, 32, v149
	v_mul_f32_e32 v82, 0xbfb8aa3b, v81
	v_exp_f32_e32 v82, v82
	s_nop 0
	v_add_f32_e32 v82, 1.0, v82
	v_rcp_f32_e32 v82, v82
	s_nop 0
	v_mul_f32_e32 v81, v81, v82
	v_mul_f32_e32 v83, v80, v81
	v_cvt_pk_bf16_f32 v80, v99, v92
	v_cvt_pk_bf16_f32 v81, v90, v91
	v_cvt_pk_bf16_f32 v82, v88, v84
	v_cvt_pk_bf16_f32 v83, v85, v83
	v_mad_i64_i32 v[84:85], s[22:23], v86, s89, v[114:115]
	v_lshl_add_u64 v[84:85], v[84:85], 0, v[116:117]
	global_store_dwordx4 v[84:85], v[80:83], off sc1
	s_nop 1
	ds_read_b32 v80, v150 offset:192
	v_mov_b32_e32 v82, v72
	v_mov_b32_e32 v83, v76
	v_mov_b32_e32 v76, v73
	s_waitcnt lgkmcnt(0)
	v_pk_mul_f32 v[82:83], v[82:83], v[80:81] op_sel_hi:[1,0]
	s_nop 0
	v_mul_f32_e32 v72, 0xbfb8aa3b, v83
	v_exp_f32_e32 v72, v72
	s_nop 0
	v_add_f32_e32 v72, 1.0, v72
	v_rcp_f32_e32 v72, v72
	s_nop 0
	v_mul_f32_e32 v72, v83, v72
	v_mul_f32_e32 v81, v82, v72
	v_pk_mul_f32 v[72:73], v[76:77], v[80:81] op_sel_hi:[1,0]
	s_nop 0
	v_mul_f32_e32 v76, 0xbfb8aa3b, v73
	v_exp_f32_e32 v76, v76
	s_nop 0
	v_add_f32_e32 v76, 1.0, v76
	v_rcp_f32_e32 v76, v76
	s_nop 0
	v_mul_f32_e32 v73, v73, v76
	v_mul_f32_e32 v76, v72, v73
	v_mov_b32_e32 v72, v74
	v_mov_b32_e32 v73, v78
	v_pk_mul_f32 v[72:73], v[72:73], v[80:81] op_sel_hi:[1,0]
	v_mov_b32_e32 v78, v75
	v_mul_f32_e32 v74, 0xbfb8aa3b, v73
	v_exp_f32_e32 v74, v74
	s_nop 0
	v_add_f32_e32 v74, 1.0, v74
	v_rcp_f32_e32 v74, v74
	s_nop 0
	v_mul_f32_e32 v73, v73, v74
	v_mul_f32_e32 v74, v72, v73
	v_pk_mul_f32 v[72:73], v[78:79], v[80:81] op_sel_hi:[1,0]
	s_nop 0
	v_mul_f32_e32 v75, 0xbfb8aa3b, v73
	v_exp_f32_e32 v75, v75
	s_nop 0
	v_add_f32_e32 v75, 1.0, v75
	v_rcp_f32_e32 v75, v75
	s_nop 0
	v_mul_f32_e32 v73, v73, v75
	v_mul_f32_e32 v75, v72, v73
	v_mov_b32_e32 v72, v64
	v_mov_b32_e32 v73, v68
	v_pk_mul_f32 v[72:73], v[72:73], v[80:81] op_sel_hi:[1,0]
	v_mov_b32_e32 v68, v65
	v_mul_f32_e32 v64, 0xbfb8aa3b, v73
	v_exp_f32_e32 v64, v64
	s_nop 0
	v_add_f32_e32 v64, 1.0, v64
	v_rcp_f32_e32 v64, v64
	s_nop 0
	v_mul_f32_e32 v64, v73, v64
	v_mul_f32_e32 v72, v72, v64
	v_pk_mul_f32 v[64:65], v[68:69], v[80:81] op_sel_hi:[1,0]
	s_nop 0
	v_mul_f32_e32 v68, 0xbfb8aa3b, v65
	v_exp_f32_e32 v68, v68
	s_nop 0
	v_add_f32_e32 v68, 1.0, v68
	v_rcp_f32_e32 v68, v68
	s_nop 0
	v_mul_f32_e32 v65, v65, v68
	v_mul_f32_e32 v68, v64, v65
	v_mov_b32_e32 v64, v66
	v_mov_b32_e32 v65, v70
	v_pk_mul_f32 v[64:65], v[64:65], v[80:81] op_sel_hi:[1,0]
	v_mov_b32_e32 v70, v67
	v_mul_f32_e32 v66, 0xbfb8aa3b, v65
	v_exp_f32_e32 v66, v66
	s_nop 0
	v_add_f32_e32 v66, 1.0, v66
	v_rcp_f32_e32 v66, v66
	s_nop 0
	v_mul_f32_e32 v65, v65, v66
	v_mul_f32_e32 v69, v64, v65
	v_pk_mul_f32 v[64:65], v[70:71], v[80:81] op_sel_hi:[1,0]
	v_or_b32_e32 v70, 48, v149
	v_mul_f32_e32 v66, 0xbfb8aa3b, v65
	v_exp_f32_e32 v66, v66
	s_nop 0
	v_add_f32_e32 v66, 1.0, v66
	v_rcp_f32_e32 v66, v66
	s_nop 0
	v_mul_f32_e32 v65, v65, v66
	v_mul_f32_e32 v67, v64, v65
	v_cvt_pk_bf16_f32 v64, v81, v76
	v_cvt_pk_bf16_f32 v65, v74, v75
	v_cvt_pk_bf16_f32 v66, v72, v68
	v_cvt_pk_bf16_f32 v67, v69, v67
	v_mad_i64_i32 v[68:69], s[22:23], v70, s89, v[114:115]
	v_lshl_add_u64 v[68:69], v[68:69], 0, v[116:117]
	global_store_dwordx4 v[68:69], v[64:67], off sc1
	s_nop 1
	ds_read_b32 v64, v150 offset:512
	v_add_u32_e32 v65, 0x80, v149
	v_mov_b32_e32 v66, v56
	v_mov_b32_e32 v67, v60
	v_mov_b32_e32 v60, v57
	s_waitcnt lgkmcnt(0)
	v_pk_mul_f32 v[66:67], v[66:67], v[64:65] op_sel_hi:[1,0]
	s_nop 0
	v_mul_f32_e32 v56, 0xbfb8aa3b, v67
	v_exp_f32_e32 v56, v56
	s_nop 0
	v_add_f32_e32 v56, 1.0, v56
	v_rcp_f32_e32 v56, v56
	s_nop 0
	v_mul_f32_e32 v56, v67, v56
	v_mul_f32_e32 v66, v66, v56
	v_pk_mul_f32 v[56:57], v[60:61], v[64:65] op_sel_hi:[1,0]
	s_nop 0
	v_mul_f32_e32 v60, 0xbfb8aa3b, v57
	v_exp_f32_e32 v60, v60
	s_nop 0
	v_add_f32_e32 v60, 1.0, v60
	v_rcp_f32_e32 v60, v60
	s_nop 0
	v_mul_f32_e32 v57, v57, v60
	v_mul_f32_e32 v60, v56, v57
	v_mov_b32_e32 v56, v58
	v_mov_b32_e32 v57, v62
	v_pk_mul_f32 v[56:57], v[56:57], v[64:65] op_sel_hi:[1,0]
	v_mov_b32_e32 v62, v59
	v_mul_f32_e32 v58, 0xbfb8aa3b, v57
	v_exp_f32_e32 v58, v58
	s_nop 0
	v_add_f32_e32 v58, 1.0, v58
	v_rcp_f32_e32 v58, v58
	s_nop 0
	v_mul_f32_e32 v57, v57, v58
	v_mul_f32_e32 v58, v56, v57
	v_pk_mul_f32 v[56:57], v[62:63], v[64:65] op_sel_hi:[1,0]
	s_nop 0
	v_mul_f32_e32 v59, 0xbfb8aa3b, v57
	v_exp_f32_e32 v59, v59
	s_nop 0
	v_add_f32_e32 v59, 1.0, v59
	v_rcp_f32_e32 v59, v59
	s_nop 0
	v_mul_f32_e32 v57, v57, v59
	v_mul_f32_e32 v59, v56, v57
	v_mov_b32_e32 v56, v48
	v_mov_b32_e32 v57, v52
	v_pk_mul_f32 v[56:57], v[56:57], v[64:65] op_sel_hi:[1,0]
	v_mov_b32_e32 v52, v49
	v_mul_f32_e32 v48, 0xbfb8aa3b, v57
	v_exp_f32_e32 v48, v48
	s_nop 0
	v_add_f32_e32 v48, 1.0, v48
	v_rcp_f32_e32 v48, v48
	s_nop 0
	v_mul_f32_e32 v48, v57, v48
	v_mul_f32_e32 v56, v56, v48
	v_pk_mul_f32 v[48:49], v[52:53], v[64:65] op_sel_hi:[1,0]
	s_nop 0
	v_mul_f32_e32 v52, 0xbfb8aa3b, v49
	v_exp_f32_e32 v52, v52
	s_nop 0
	v_add_f32_e32 v52, 1.0, v52
	v_rcp_f32_e32 v52, v52
	s_nop 0
	v_mul_f32_e32 v49, v49, v52
	v_mul_f32_e32 v52, v48, v49
	v_mov_b32_e32 v48, v50
	v_mov_b32_e32 v49, v54
	v_pk_mul_f32 v[48:49], v[48:49], v[64:65] op_sel_hi:[1,0]
	v_mov_b32_e32 v54, v51
	v_mul_f32_e32 v50, 0xbfb8aa3b, v49
	v_exp_f32_e32 v50, v50
	s_nop 0
	v_add_f32_e32 v50, 1.0, v50
	v_rcp_f32_e32 v50, v50
	s_nop 0
	v_mul_f32_e32 v49, v49, v50
	v_mul_f32_e32 v53, v48, v49
	v_pk_mul_f32 v[48:49], v[54:55], v[64:65] op_sel_hi:[1,0]
	s_nop 0
	v_mul_f32_e32 v50, 0xbfb8aa3b, v49
	v_exp_f32_e32 v50, v50
	s_nop 0
	v_add_f32_e32 v50, 1.0, v50
	v_rcp_f32_e32 v50, v50
	s_nop 0
	v_mul_f32_e32 v49, v49, v50
	v_mul_f32_e32 v51, v48, v49
	v_cvt_pk_bf16_f32 v48, v66, v60
	v_cvt_pk_bf16_f32 v49, v58, v59
	v_cvt_pk_bf16_f32 v50, v56, v52
	v_cvt_pk_bf16_f32 v51, v53, v51
	v_mad_i64_i32 v[52:53], s[22:23], v65, s89, v[114:115]
	v_lshl_add_u64 v[52:53], v[52:53], 0, v[116:117]
	global_store_dwordx4 v[52:53], v[48:51], off sc1
	s_nop 1
	ds_read_b32 v48, v150 offset:576
	v_mov_b32_e32 v50, v40
	v_mov_b32_e32 v51, v44
	v_mov_b32_e32 v44, v41
	s_waitcnt lgkmcnt(0)
	v_pk_mul_f32 v[50:51], v[50:51], v[48:49] op_sel_hi:[1,0]
	s_nop 0
	v_mul_f32_e32 v40, 0xbfb8aa3b, v51
	v_exp_f32_e32 v40, v40
	s_nop 0
	v_add_f32_e32 v40, 1.0, v40
	v_rcp_f32_e32 v40, v40
	s_nop 0
	v_mul_f32_e32 v40, v51, v40
	v_mul_f32_e32 v49, v50, v40
	v_pk_mul_f32 v[40:41], v[44:45], v[48:49] op_sel_hi:[1,0]
	s_nop 0
	v_mul_f32_e32 v44, 0xbfb8aa3b, v41
	v_exp_f32_e32 v44, v44
	s_nop 0
	v_add_f32_e32 v44, 1.0, v44
	v_rcp_f32_e32 v44, v44
	s_nop 0
	v_mul_f32_e32 v41, v41, v44
	v_mul_f32_e32 v44, v40, v41
	v_mov_b32_e32 v40, v42
	v_mov_b32_e32 v41, v46
	v_pk_mul_f32 v[40:41], v[40:41], v[48:49] op_sel_hi:[1,0]
	v_mov_b32_e32 v46, v43
	v_mul_f32_e32 v42, 0xbfb8aa3b, v41
	v_exp_f32_e32 v42, v42
	s_nop 0
	v_add_f32_e32 v42, 1.0, v42
	v_rcp_f32_e32 v42, v42
	s_nop 0
	v_mul_f32_e32 v41, v41, v42
	v_mul_f32_e32 v42, v40, v41
	v_pk_mul_f32 v[40:41], v[46:47], v[48:49] op_sel_hi:[1,0]
	s_nop 0
	v_mul_f32_e32 v43, 0xbfb8aa3b, v41
	v_exp_f32_e32 v43, v43
	s_nop 0
	v_add_f32_e32 v43, 1.0, v43
	v_rcp_f32_e32 v43, v43
	s_nop 0
	v_mul_f32_e32 v41, v41, v43
	v_mul_f32_e32 v43, v40, v41
	v_mov_b32_e32 v40, v32
	v_mov_b32_e32 v41, v36
	v_pk_mul_f32 v[40:41], v[40:41], v[48:49] op_sel_hi:[1,0]
	v_mov_b32_e32 v36, v33
	v_mul_f32_e32 v32, 0xbfb8aa3b, v41
	v_exp_f32_e32 v32, v32
	s_nop 0
	v_add_f32_e32 v32, 1.0, v32
	v_rcp_f32_e32 v32, v32
	s_nop 0
	v_mul_f32_e32 v32, v41, v32
	v_mul_f32_e32 v40, v40, v32
	v_pk_mul_f32 v[32:33], v[36:37], v[48:49] op_sel_hi:[1,0]
	s_nop 0
	v_mul_f32_e32 v36, 0xbfb8aa3b, v33
	v_exp_f32_e32 v36, v36
	s_nop 0
	v_add_f32_e32 v36, 1.0, v36
	v_rcp_f32_e32 v36, v36
	s_nop 0
	v_mul_f32_e32 v33, v33, v36
	v_mul_f32_e32 v36, v32, v33
	v_mov_b32_e32 v32, v34
	v_mov_b32_e32 v33, v38
	v_pk_mul_f32 v[32:33], v[32:33], v[48:49] op_sel_hi:[1,0]
	v_mov_b32_e32 v38, v35
	v_mul_f32_e32 v34, 0xbfb8aa3b, v33
	v_exp_f32_e32 v34, v34
	s_nop 0
	v_add_f32_e32 v34, 1.0, v34
	v_rcp_f32_e32 v34, v34
	s_nop 0
	v_mul_f32_e32 v33, v33, v34
	v_mul_f32_e32 v37, v32, v33
	v_pk_mul_f32 v[32:33], v[38:39], v[48:49] op_sel_hi:[1,0]
	v_add_u32_e32 v38, 0x90, v149
	v_mul_f32_e32 v34, 0xbfb8aa3b, v33
	v_exp_f32_e32 v34, v34
	s_nop 0
	v_add_f32_e32 v34, 1.0, v34
	v_rcp_f32_e32 v34, v34
	s_nop 0
	v_mul_f32_e32 v33, v33, v34
	v_mul_f32_e32 v35, v32, v33
	v_cvt_pk_bf16_f32 v32, v49, v44
	v_cvt_pk_bf16_f32 v33, v42, v43
	v_cvt_pk_bf16_f32 v34, v40, v36
	v_cvt_pk_bf16_f32 v35, v37, v35
	v_mad_i64_i32 v[36:37], s[22:23], v38, s89, v[114:115]
	v_lshl_add_u64 v[36:37], v[36:37], 0, v[116:117]
	global_store_dwordx4 v[36:37], v[32:35], off sc1
	s_nop 1
	ds_read_b32 v32, v150 offset:640
	v_mov_b32_e32 v34, v24
	v_mov_b32_e32 v35, v28
	v_mov_b32_e32 v28, v25
	s_waitcnt lgkmcnt(0)
	v_pk_mul_f32 v[34:35], v[34:35], v[32:33] op_sel_hi:[1,0]
	s_nop 0
	v_mul_f32_e32 v24, 0xbfb8aa3b, v35
	v_exp_f32_e32 v24, v24
	s_nop 0
	v_add_f32_e32 v24, 1.0, v24
	v_rcp_f32_e32 v24, v24
	s_nop 0
	v_mul_f32_e32 v24, v35, v24
	v_mul_f32_e32 v33, v34, v24
	v_pk_mul_f32 v[24:25], v[28:29], v[32:33] op_sel_hi:[1,0]
	s_nop 0
	v_mul_f32_e32 v28, 0xbfb8aa3b, v25
	v_exp_f32_e32 v28, v28
	s_nop 0
	v_add_f32_e32 v28, 1.0, v28
	v_rcp_f32_e32 v28, v28
	s_nop 0
	v_mul_f32_e32 v25, v25, v28
	v_mul_f32_e32 v28, v24, v25
	v_mov_b32_e32 v24, v26
	v_mov_b32_e32 v25, v30
	v_pk_mul_f32 v[24:25], v[24:25], v[32:33] op_sel_hi:[1,0]
	v_mov_b32_e32 v30, v27
	v_mul_f32_e32 v26, 0xbfb8aa3b, v25
	v_exp_f32_e32 v26, v26
	s_nop 0
	v_add_f32_e32 v26, 1.0, v26
	v_rcp_f32_e32 v26, v26
	s_nop 0
	v_mul_f32_e32 v25, v25, v26
	v_mul_f32_e32 v26, v24, v25
	v_pk_mul_f32 v[24:25], v[30:31], v[32:33] op_sel_hi:[1,0]
	s_nop 0
	v_mul_f32_e32 v27, 0xbfb8aa3b, v25
	v_exp_f32_e32 v27, v27
	s_nop 0
	v_add_f32_e32 v27, 1.0, v27
	v_rcp_f32_e32 v27, v27
	s_nop 0
	v_mul_f32_e32 v25, v25, v27
	v_mul_f32_e32 v27, v24, v25
	v_mov_b32_e32 v24, v16
	v_mov_b32_e32 v25, v20
	v_pk_mul_f32 v[24:25], v[24:25], v[32:33] op_sel_hi:[1,0]
	v_mov_b32_e32 v20, v17
	v_mul_f32_e32 v16, 0xbfb8aa3b, v25
	v_exp_f32_e32 v16, v16
	s_nop 0
	v_add_f32_e32 v16, 1.0, v16
	v_rcp_f32_e32 v16, v16
	s_nop 0
	v_mul_f32_e32 v16, v25, v16
	v_mul_f32_e32 v24, v24, v16
	v_pk_mul_f32 v[16:17], v[20:21], v[32:33] op_sel_hi:[1,0]
	s_nop 0
	v_mul_f32_e32 v20, 0xbfb8aa3b, v17
	v_exp_f32_e32 v20, v20
	s_nop 0
	v_add_f32_e32 v20, 1.0, v20
	v_rcp_f32_e32 v20, v20
	s_nop 0
	v_mul_f32_e32 v17, v17, v20
	v_mul_f32_e32 v20, v16, v17
	v_mov_b32_e32 v16, v18
	v_mov_b32_e32 v17, v22
	v_pk_mul_f32 v[16:17], v[16:17], v[32:33] op_sel_hi:[1,0]
	v_mov_b32_e32 v22, v19
	v_mul_f32_e32 v18, 0xbfb8aa3b, v17
	v_exp_f32_e32 v18, v18
	s_nop 0
	v_add_f32_e32 v18, 1.0, v18
	v_rcp_f32_e32 v18, v18
	s_nop 0
	v_mul_f32_e32 v17, v17, v18
	v_mul_f32_e32 v21, v16, v17
	v_pk_mul_f32 v[16:17], v[22:23], v[32:33] op_sel_hi:[1,0]
	v_add_u32_e32 v22, 0xa0, v149
	v_mul_f32_e32 v18, 0xbfb8aa3b, v17
	v_exp_f32_e32 v18, v18
	s_nop 0
	v_add_f32_e32 v18, 1.0, v18
	v_rcp_f32_e32 v18, v18
	s_nop 0
	v_mul_f32_e32 v17, v17, v18
	v_mul_f32_e32 v19, v16, v17
	v_cvt_pk_bf16_f32 v16, v33, v28
	v_cvt_pk_bf16_f32 v17, v26, v27
	v_cvt_pk_bf16_f32 v18, v24, v20
	v_cvt_pk_bf16_f32 v19, v21, v19
	v_mad_i64_i32 v[20:21], s[22:23], v22, s89, v[114:115]
	v_lshl_add_u64 v[20:21], v[20:21], 0, v[116:117]
	global_store_dwordx4 v[20:21], v[16:19], off sc1
	s_nop 1
	ds_read_b32 v16, v150 offset:704
	v_mov_b32_e32 v18, v8
	v_mov_b32_e32 v19, v12
	v_mov_b32_e32 v12, v9
	s_waitcnt lgkmcnt(0)
	v_pk_mul_f32 v[18:19], v[18:19], v[16:17] op_sel_hi:[1,0]
	s_nop 0
	v_mul_f32_e32 v8, 0xbfb8aa3b, v19
	v_exp_f32_e32 v8, v8
	s_nop 0
	v_add_f32_e32 v8, 1.0, v8
	v_rcp_f32_e32 v8, v8
	s_nop 0
	v_mul_f32_e32 v8, v19, v8
	v_mul_f32_e32 v17, v18, v8
	v_pk_mul_f32 v[8:9], v[12:13], v[16:17] op_sel_hi:[1,0]
	s_nop 0
	v_mul_f32_e32 v12, 0xbfb8aa3b, v9
	v_exp_f32_e32 v12, v12
	s_nop 0
	v_add_f32_e32 v12, 1.0, v12
	v_rcp_f32_e32 v12, v12
	s_nop 0
	v_mul_f32_e32 v9, v9, v12
	v_mul_f32_e32 v12, v8, v9
	v_mov_b32_e32 v8, v10
	v_mov_b32_e32 v9, v14
	v_pk_mul_f32 v[8:9], v[8:9], v[16:17] op_sel_hi:[1,0]
	v_mov_b32_e32 v14, v11
	v_mul_f32_e32 v10, 0xbfb8aa3b, v9
	v_exp_f32_e32 v10, v10
	s_nop 0
	v_add_f32_e32 v10, 1.0, v10
	v_rcp_f32_e32 v10, v10
	s_nop 0
	v_mul_f32_e32 v9, v9, v10
	v_mul_f32_e32 v10, v8, v9
	v_pk_mul_f32 v[8:9], v[14:15], v[16:17] op_sel_hi:[1,0]
	s_nop 0
	v_mul_f32_e32 v11, 0xbfb8aa3b, v9
	v_exp_f32_e32 v11, v11
	s_nop 0
	v_add_f32_e32 v11, 1.0, v11
	v_rcp_f32_e32 v11, v11
	s_nop 0
	v_mul_f32_e32 v9, v9, v11
	v_mul_f32_e32 v11, v8, v9
	v_mov_b32_e32 v8, v0
	v_mov_b32_e32 v9, v4
	v_pk_mul_f32 v[8:9], v[8:9], v[16:17] op_sel_hi:[1,0]
	v_mov_b32_e32 v4, v1
	v_mul_f32_e32 v0, 0xbfb8aa3b, v9
	v_exp_f32_e32 v0, v0
	s_nop 0
	v_add_f32_e32 v0, 1.0, v0
	v_rcp_f32_e32 v0, v0
	s_nop 0
	v_mul_f32_e32 v0, v9, v0
	v_mul_f32_e32 v8, v8, v0
	v_pk_mul_f32 v[0:1], v[4:5], v[16:17] op_sel_hi:[1,0]
	s_nop 0
	v_mul_f32_e32 v4, 0xbfb8aa3b, v1
	v_exp_f32_e32 v4, v4
	s_nop 0
	v_add_f32_e32 v4, 1.0, v4
	v_rcp_f32_e32 v4, v4
	s_nop 0
	v_mul_f32_e32 v1, v1, v4
	v_mul_f32_e32 v4, v0, v1
	v_mov_b32_e32 v0, v2
	v_mov_b32_e32 v1, v6
	v_pk_mul_f32 v[0:1], v[0:1], v[16:17] op_sel_hi:[1,0]
	v_mov_b32_e32 v6, v3
	v_mul_f32_e32 v2, 0xbfb8aa3b, v1
	v_exp_f32_e32 v2, v2
	s_nop 0
	v_add_f32_e32 v2, 1.0, v2
	v_rcp_f32_e32 v2, v2
	s_nop 0
	v_mul_f32_e32 v1, v1, v2
	v_mul_f32_e32 v5, v0, v1
	v_pk_mul_f32 v[0:1], v[6:7], v[16:17] op_sel_hi:[1,0]
	v_add_u32_e32 v6, 0xb0, v149
	v_mul_f32_e32 v2, 0xbfb8aa3b, v1
	v_exp_f32_e32 v2, v2
	s_nop 0
	v_add_f32_e32 v2, 1.0, v2
	v_rcp_f32_e32 v2, v2
	s_nop 0
	v_mul_f32_e32 v1, v1, v2
	v_mul_f32_e32 v3, v0, v1
	v_cvt_pk_bf16_f32 v0, v17, v12
	v_cvt_pk_bf16_f32 v1, v10, v11
	v_cvt_pk_bf16_f32 v2, v8, v4
	v_cvt_pk_bf16_f32 v3, v5, v3
	v_mad_i64_i32 v[4:5], s[22:23], v6, s89, v[114:115]
	v_lshl_add_u64 v[4:5], v[4:5], 0, v[116:117]
	global_store_dwordx4 v[4:5], v[0:3], off sc1
	s_nop 1
	s_mov_b64 s[22:23], -1
	s_cbranch_vccnz .LBB0_142
	s_andn2_b64 vcc, exec, s[6:7]
	s_cbranch_vccnz .LBB0_141
	s_barrier
	s_branch .LBB0_141
